# GLU GEMM: L2 warm-up loads of the epilogue operand tiles issued before the K-loop
# baseline (speedup 1.0000x reference)
; template <class Epi, class Sched>
; __device__ __forceinline__ void gemm_phase(const int TID, LAS unsigned char* lds, const int lda, const int ldb, const Sched& S, const Epi& E) {
;     ...
;         for (int a = 0; a < 2; ++a)
; #pragma unroll
;             for (int b = 0; b < 2; ++b)
; #pragma unroll
;                 for (int m = 0; m < 4; ++m)
; #pragma unroll
;                     for (int n = 0; n < 2; ++n) acc[a][b][m][n] = (f32x4){0.f, 0.f, 0.f, 0.f};
.LBB0_294:
	s_add_u32 s23, s54, 0x100
	s_addc_u32 s47, s55, 0
	s_add_u32 s28, s28, 0x20080
	v_mov_b32_e32 v0, 0
	s_addc_u32 s29, s29, 0
	s_mov_b32 s49, -2
	v_mov_b32_e32 v1, v0
	v_mov_b32_e32 v2, v0
	v_mov_b32_e32 v3, v0
	v_mov_b32_e32 v4, v0
	v_mov_b32_e32 v5, v0
	v_mov_b32_e32 v6, v0
	v_mov_b32_e32 v7, v0
	v_mov_b32_e32 v22, v0
	v_mov_b32_e32 v23, v0
	v_mov_b32_e32 v24, v0
	v_mov_b32_e32 v25, v0
	v_mov_b32_e32 v26, v0
	v_mov_b32_e32 v27, v0
	v_mov_b32_e32 v28, v0
	v_mov_b32_e32 v29, v0
	v_mov_b32_e32 v54, v0
	v_mov_b32_e32 v55, v0
	v_mov_b32_e32 v56, v0
	v_mov_b32_e32 v57, v0
	v_mov_b32_e32 v58, v0
	v_mov_b32_e32 v59, v0
	v_mov_b32_e32 v60, v0
	v_mov_b32_e32 v61, v0
	s_waitcnt lgkmcnt(0)
	v_mov_b32_e32 v70, v0
	v_mov_b32_e32 v71, v0
	v_mov_b32_e32 v72, v0
	v_mov_b32_e32 v73, v0
	v_mov_b32_e32 v74, v0
	v_mov_b32_e32 v75, v0
	v_mov_b32_e32 v76, v0
	v_mov_b32_e32 v77, v0
	v_mov_b32_e32 v8, v0
	v_mov_b32_e32 v9, v0
	v_mov_b32_e32 v10, v0
	v_mov_b32_e32 v11, v0
	v_mov_b32_e32 v18, v0
	v_mov_b32_e32 v19, v0
	v_mov_b32_e32 v20, v0
	v_mov_b32_e32 v21, v0
	v_mov_b32_e32 v34, v0
	v_mov_b32_e32 v35, v0
	v_mov_b32_e32 v36, v0
	v_mov_b32_e32 v37, v0
	v_mov_b32_e32 v42, v0
	v_mov_b32_e32 v43, v0
	v_mov_b32_e32 v44, v0
	v_mov_b32_e32 v45, v0
	v_mov_b32_e32 v62, v0
	v_mov_b32_e32 v63, v0
	v_mov_b32_e32 v64, v0
	v_mov_b32_e32 v65, v0
	v_mov_b32_e32 v66, v0
	v_mov_b32_e32 v67, v0
	v_mov_b32_e32 v68, v0
	v_mov_b32_e32 v69, v0
	v_mov_b32_e32 v78, v0
	v_mov_b32_e32 v79, v0
	v_mov_b32_e32 v80, v0
	v_mov_b32_e32 v81, v0
	v_mov_b32_e32 v82, v0
	v_mov_b32_e32 v83, v0
	v_mov_b32_e32 v84, v0
	v_mov_b32_e32 v85, v0
	v_mov_b32_e32 v86, v0
	v_mov_b32_e32 v87, v0
	v_mov_b32_e32 v88, v0
	v_mov_b32_e32 v89, v0
	v_mov_b32_e32 v90, v0
	v_mov_b32_e32 v91, v0
	v_mov_b32_e32 v92, v0
	v_mov_b32_e32 v93, v0
	v_mov_b32_e32 v102, v0
	v_mov_b32_e32 v103, v0
	v_mov_b32_e32 v104, v0
	v_mov_b32_e32 v105, v0
	v_mov_b32_e32 v106, v0
	v_mov_b32_e32 v107, v0
	v_mov_b32_e32 v108, v0
	v_mov_b32_e32 v109, v0
	v_mov_b32_e32 v118, v0
	s_waitcnt vmcnt(0)
	v_mov_b32_e32 v119, v0
	v_mov_b32_e32 v120, v0
	v_mov_b32_e32 v121, v0
	v_mov_b32_e32 v122, v0
	v_mov_b32_e32 v123, v0
	v_mov_b32_e32 v124, v0
	v_mov_b32_e32 v125, v0
	v_mov_b32_e32 v134, v0
	v_mov_b32_e32 v135, v0
	v_mov_b32_e32 v136, v0
	v_mov_b32_e32 v137, v0
	v_mov_b32_e32 v138, v0
	v_mov_b32_e32 v139, v0
	v_mov_b32_e32 v140, v0
	v_mov_b32_e32 v141, v0
	v_mov_b32_e32 v94, v0
	v_mov_b32_e32 v95, v0
	v_mov_b32_e32 v96, v0
	v_mov_b32_e32 v97, v0
	v_mov_b32_e32 v98, v0
	v_mov_b32_e32 v99, v0
	v_mov_b32_e32 v100, v0
	v_mov_b32_e32 v101, v0
	v_mov_b32_e32 v110, v0
	v_mov_b32_e32 v111, v0
	v_mov_b32_e32 v112, v0
	v_mov_b32_e32 v113, v0
	v_mov_b32_e32 v114, v0
	v_mov_b32_e32 v115, v0
	v_mov_b32_e32 v116, v0
	v_mov_b32_e32 v117, v0
	v_mov_b32_e32 v126, v0
	v_mov_b32_e32 v127, v0
	v_mov_b32_e32 v128, v0
	v_mov_b32_e32 v129, v0
	v_mov_b32_e32 v130, v0
	v_mov_b32_e32 v131, v0
	v_mov_b32_e32 v132, v0
	v_mov_b32_e32 v133, v0
	v_mov_b32_e32 v150, v0
	v_mov_b32_e32 v151, v0
	v_mov_b32_e32 v152, v0
	v_mov_b32_e32 v153, v0
	v_mov_b32_e32 v162, v0
	v_mov_b32_e32 v163, v0
	v_mov_b32_e32 v164, v0
	v_mov_b32_e32 v165, v0
	v_lshrrev_b32_e32 v243, 1, v194
	v_and_b32_e32 v241, 1, v194
	v_lshl_add_u32 v243, s2, 8, v243
	s_lshl_b32 s8, s21, 9
	v_lshlrev_b32_e32 v241, 8, v241
	v_add_u32_e32 v241, s8, v241
	v_mad_u32_u24 v242, v243, s4, v241
	v_lshl_add_u32 v241, v243, 10, v241
	global_load_dword v240, v241, s[0:1]
	global_load_dword v240, v241, s[0:1] offset:128
	global_load_dword v240, v242, s[40:41] offset:1024
	global_load_dword v240, v242, s[40:41] offset:1152
